# v48 + QKV epilogue: 32 dwordx2 stores per wave merged into 16 dwordx4 via v_permlane16_swap (asm guide 7.3, 16-lane form)
# speedup vs baseline: 1.0058x; 1.0023x over previous
.LBB0_316:
	s_waitcnt lgkmcnt(6)
	v_fmamk_f32 v18, v218, 0x39800000, v237
	v_mul_f32_e32 v19, 0x4f800000, v18
	v_cmp_gt_f32_e32 vcc, s73, v18
	v_cvt_f32_i32_e32 v27, v171
	v_cvt_f32_i32_e32 v29, v173
	v_cndmask_b32_e32 v18, v18, v19, vcc
	v_sqrt_f32_e32 v19, v18
	v_cvt_f32_i32_e32 v28, v172
	v_cvt_f32_i32_e32 v26, v170
	s_lshl_b32 s18, s40, 1
	v_add_u32_e32 v20, -1, v19
	v_fma_f32 v22, -v20, v19, v18
	v_add_u32_e32 v21, 1, v19
	v_cmp_ge_f32_e64 s[8:9], 0, v22
	v_cvt_f32_i32_e32 v25, v177
	v_cvt_f32_i32_e32 v24, v176
	v_cndmask_b32_e64 v20, v19, v20, s[8:9]
	v_fma_f32 v19, -v21, v19, v18
	v_cmp_lt_f32_e64 s[8:9], 0, v19
	s_or_b32 s52, s18, 1
	s_nop 0
	v_cndmask_b32_e64 v19, v20, v21, s[8:9]
	v_mul_f32_e32 v20, 0x37800000, v19
	v_cndmask_b32_e32 v19, v19, v20, vcc
	v_cmp_class_f32_e32 vcc, v18, v238
	s_nop 1
	v_cndmask_b32_e32 v18, v19, v18, vcc
	v_div_scale_f32 v19, s[8:9], v18, v18, v219
	v_rcp_f32_e32 v20, v19
	s_mul_hi_i32 s8, s40, 0x2aaaaaab
	s_lshr_b32 s9, s8, 31
	s_ashr_i32 s31, s8, 2
	v_fma_f32 v21, -v19, v20, 1.0
	v_fmac_f32_e32 v20, v21, v20
	v_div_scale_f32 v21, vcc, v219, v18, v219
	v_mul_f32_e32 v22, v21, v20
	v_fma_f32 v23, -v19, v22, v21
	v_fmac_f32_e32 v22, v23, v20
	v_fma_f32 v19, -v19, v22, v21
	v_div_fmas_f32 v19, v19, v20, v22
	v_div_fixup_f32 v18, v19, v18, v219
	v_ashrrev_i32_e32 v19, 12, v216
	s_add_i32 s31, s31, s9
	v_lshlrev_b32_e32 v22, 8, v216
	v_add_u32_e32 v20, s31, v19
	v_and_b32_e32 v194, 0xfff00, v22
	v_cvt_f32_i32_e32 v23, v175
	v_cvt_f32_i32_e32 v22, v174
	v_mad_u64_u32 v[20:21], s[8:9], v20, 48, s[18:19]
	v_ashrrev_i32_e32 v21, 31, v20
	v_lshlrev_b64 v[20:21], 20, v[20:21]
	v_pk_mul_f32 v[28:29], v[18:19], v[28:29] op_sel_hi:[0,1]
	v_pk_mul_f32 v[26:27], v[18:19], v[26:27] op_sel_hi:[0,1]
	v_lshl_add_u64 v[20:21], s[16:17], 0, v[20:21]
	v_pk_mul_f32 v[24:25], v[18:19], v[24:25] op_sel_hi:[0,1]
	v_pk_mul_f32 v[22:23], v[18:19], v[22:23] op_sel_hi:[0,1]
	v_pk_mul_f32 v[26:27], v[106:107], v[26:27]
	v_pk_mul_f32 v[28:29], v[108:109], v[28:29]
	v_lshl_add_u64 v[20:21], v[20:21], 0, v[194:195]
	s_waitcnt lgkmcnt(4)
	v_pk_mul_f32 v[22:23], v[110:111], v[22:23]
	v_pk_mul_f32 v[24:25], v[112:113], v[24:25]
	v_pk_mul_f32 v[30:31], v[28:29], v[4:5]
	v_pk_mul_f32 v[32:33], v[26:27], v[2:3]
	v_pk_mul_f32 v[170:171], v[28:29], v[192:193]
	v_pk_mul_f32 v[172:173], v[26:27], v[190:191]
	v_lshl_add_u64 v[20:21], v[20:21], 0, s[26:27]
	v_lshlrev_b64 v[218:219], 1, v[214:215]
	v_mbcnt_lo_u32_b32 v250, -1, 0
	v_mbcnt_hi_u32_b32 v250, -1, v250
	v_and_b32_e32 v250, 16, v250
	v_lshrrev_b32_e32 v251, 1, v250
	v_add3_u32 v218, v218, v250, v251
	v_pk_fma_f32 v[32:33], v[22:23], v[190:191], v[32:33] neg_lo:[0,0,1] neg_hi:[0,0,1]
	v_pk_fma_f32 v[30:31], v[24:25], v[192:193], v[30:31] neg_lo:[0,0,1] neg_hi:[0,0,1]
	v_pk_fma_f32 v[172:173], v[22:23], v[2:3], v[172:173]
	v_pk_fma_f32 v[170:171], v[24:25], v[4:5], v[170:171]
	v_lshl_add_u64 v[20:21], v[20:21], 0, v[218:219]
	v_cndmask_b32_e64 v175, v25, v31, s[4:5]
	v_cndmask_b32_e64 v174, v24, v30, s[4:5]
	v_cndmask_b32_e64 v177, v23, v33, s[4:5]
	v_cndmask_b32_e64 v176, v22, v32, s[4:5]
	v_cndmask_b32_e64 v171, v29, v171, s[4:5]
	v_cndmask_b32_e64 v170, v28, v170, s[4:5]
	v_cndmask_b32_e64 v173, v27, v173, s[4:5]
	v_cndmask_b32_e64 v172, v26, v172, s[4:5]
	v_cvt_pk_bf16_f32 v22, v176, v177
	v_cvt_pk_bf16_f32 v23, v174, v175
	v_cvt_pk_bf16_f32 v24, v172, v173
	v_cvt_pk_bf16_f32 v25, v170, v171
	s_nop 1
	v_permlane16_swap_b32_e32 v22, v24
	v_permlane16_swap_b32_e32 v23, v25
	global_store_dwordx4 v[20:21], v[22:25], off
	s_nop 1
	s_mul_hi_i32 s8, s52, 0x2aaaaaab
	v_cvt_f32_i32_e32 v23, v167
	v_cvt_f32_i32_e32 v22, v166
	v_cvt_f32_i32_e32 v25, v169
	v_cvt_f32_i32_e32 v24, v168
	v_cvt_f32_i32_e32 v27, v163
	v_cvt_f32_i32_e32 v29, v165
	v_cvt_f32_i32_e32 v28, v164
	v_cvt_f32_i32_e32 v26, v162
	s_lshr_b32 s9, s8, 31
	s_ashr_i32 s35, s8, 3
	s_add_i32 s35, s35, s9
	v_add_u32_e32 v19, s35, v19
	v_mad_u64_u32 v[20:21], s[8:9], v19, 48, s[52:53]
	v_pk_mul_f32 v[24:25], v[18:19], v[24:25] op_sel_hi:[0,1]
	v_pk_mul_f32 v[22:23], v[18:19], v[22:23] op_sel_hi:[0,1]
	v_pk_mul_f32 v[28:29], v[18:19], v[28:29] op_sel_hi:[0,1]
	v_pk_mul_f32 v[18:19], v[18:19], v[26:27] op_sel_hi:[0,1]
	v_pk_mul_f32 v[18:19], v[98:99], v[18:19]
	v_pk_mul_f32 v[22:23], v[102:103], v[22:23]
	v_pk_mul_f32 v[26:27], v[100:101], v[28:29]
	v_pk_mul_f32 v[162:163], v[18:19], v[190:191]
	v_pk_mul_f32 v[24:25], v[104:105], v[24:25]
	v_pk_mul_f32 v[30:31], v[18:19], v[2:3]
	v_pk_mul_f32 v[32:33], v[26:27], v[192:193]
	v_pk_fma_f32 v[2:3], v[22:23], v[2:3], v[162:163]
	v_pk_mul_f32 v[28:29], v[26:27], v[4:5]
	v_pk_fma_f32 v[4:5], v[24:25], v[4:5], v[32:33]
	v_cndmask_b32_e64 v165, v19, v3, s[4:5]
	s_waitcnt lgkmcnt(2)
	v_fmamk_f32 v3, v245, 0x39800000, v237
	v_cndmask_b32_e64 v162, v26, v4, s[4:5]
	v_mul_f32_e32 v4, 0x4f800000, v3
	v_cmp_gt_f32_e32 vcc, s73, v3
	v_cndmask_b32_e64 v164, v18, v2, s[4:5]
	v_pk_fma_f32 v[30:31], v[22:23], v[190:191], v[30:31] neg_lo:[0,0,1] neg_hi:[0,0,1]
	v_cndmask_b32_e32 v18, v3, v4, vcc
	v_sqrt_f32_e32 v19, v18
	v_cndmask_b32_e64 v168, v22, v30, s[4:5]
	v_cndmask_b32_e64 v169, v23, v31, s[4:5]
	v_ashrrev_i32_e32 v21, 31, v20
	v_add_u32_e32 v22, -1, v19
	v_fma_f32 v23, -v22, v19, v18
	v_cmp_ge_f32_e64 s[8:9], 0, v23
	v_add_u32_e32 v23, 1, v19
	v_lshlrev_b64 v[20:21], 20, v[20:21]
	v_cndmask_b32_e64 v22, v19, v22, s[8:9]
	v_fma_f32 v19, -v23, v19, v18
	v_cmp_lt_f32_e64 s[8:9], 0, v19
	v_lshl_add_u64 v[20:21], s[16:17], 0, v[20:21]
	v_lshl_add_u64 v[20:21], v[20:21], 0, v[194:195]
	v_cndmask_b32_e64 v19, v22, v23, s[8:9]
	v_mul_f32_e32 v22, 0x37800000, v19
	v_cndmask_b32_e32 v19, v19, v22, vcc
	v_cmp_class_f32_e32 vcc, v18, v238
	v_lshl_add_u64 v[20:21], v[20:21], 0, s[26:27]
	v_pk_fma_f32 v[28:29], v[24:25], v[192:193], v[28:29] neg_lo:[0,0,1] neg_hi:[0,0,1]
	v_cndmask_b32_e32 v18, v19, v18, vcc
	v_div_scale_f32 v19, s[8:9], v18, v18, v224
	v_rcp_f32_e32 v22, v19
	v_lshl_add_u64 v[20:21], v[20:21], 0, v[218:219]
	v_cndmask_b32_e64 v167, v25, v29, s[4:5]
	v_cndmask_b32_e64 v166, v24, v28, s[4:5]
	v_cvt_pk_bf16_f32 v2, v168, v169
	v_cvt_pk_bf16_f32 v3, v166, v167
	v_cndmask_b32_e64 v163, v27, v5, s[4:5]
	v_cvt_pk_bf16_f32 v4, v164, v165
	v_cvt_pk_bf16_f32 v5, v162, v163
	s_nop 1
	v_permlane16_swap_b32_e32 v2, v4
	v_permlane16_swap_b32_e32 v3, v5
	global_store_dwordx4 v[20:21], v[2:5], off
	s_nop 1
	v_fma_f32 v2, -v19, v22, 1.0
	v_fmac_f32_e32 v22, v2, v22
	v_div_scale_f32 v2, vcc, v224, v18, v224
	v_mul_f32_e32 v4, v2, v22
	v_fma_f32 v5, -v19, v4, v2
	v_fmac_f32_e32 v4, v5, v22
	v_add_u32_e32 v3, 16, v216
	v_fma_f32 v2, -v19, v4, v2
	v_div_fmas_f32 v2, v2, v22, v4
	v_ashrrev_i32_e32 v190, 12, v3
	v_cvt_f32_i32_e32 v23, v155
	v_cvt_f32_i32_e32 v25, v157
	v_cvt_f32_i32_e32 v24, v156
	v_cvt_f32_i32_e32 v22, v154
	v_div_fixup_f32 v2, v2, v18, v224
	v_add_u32_e32 v4, s31, v190
	v_cvt_f32_i32_e32 v19, v159
	v_cvt_f32_i32_e32 v18, v158
	v_cvt_f32_i32_e32 v21, v161
	v_cvt_f32_i32_e32 v20, v160
	v_mad_u64_u32 v[4:5], s[8:9], v4, 48, s[18:19]
	v_ashrrev_i32_e32 v5, 31, v4
	v_lshlrev_b32_e32 v3, 8, v3
	v_lshlrev_b64 v[4:5], 20, v[4:5]
	v_pk_mul_f32 v[24:25], v[2:3], v[24:25] op_sel_hi:[0,1]
	v_pk_mul_f32 v[22:23], v[2:3], v[22:23] op_sel_hi:[0,1]
	v_lshl_add_u64 v[4:5], s[16:17], 0, v[4:5]
	v_and_b32_e32 v194, 0xfff00, v3
	v_pk_mul_f32 v[20:21], v[2:3], v[20:21] op_sel_hi:[0,1]
	v_pk_mul_f32 v[18:19], v[2:3], v[18:19] op_sel_hi:[0,1]
	v_pk_mul_f32 v[22:23], v[106:107], v[22:23]
	v_pk_mul_f32 v[24:25], v[108:109], v[24:25]
	v_lshl_add_u64 v[4:5], v[4:5], 0, v[194:195]
	v_pk_mul_f32 v[18:19], v[110:111], v[18:19]
	v_pk_mul_f32 v[20:21], v[112:113], v[20:21]
	v_pk_mul_f32 v[26:27], v[24:25], v[8:9]
	v_pk_mul_f32 v[28:29], v[22:23], v[6:7]
	v_pk_mul_f32 v[30:31], v[24:25], v[188:189]
	v_pk_mul_f32 v[32:33], v[22:23], v[186:187]
	v_lshl_add_u64 v[4:5], v[4:5], 0, s[26:27]
	v_pk_fma_f32 v[28:29], v[18:19], v[186:187], v[28:29] neg_lo:[0,0,1] neg_hi:[0,0,1]
	v_pk_fma_f32 v[26:27], v[20:21], v[188:189], v[26:27] neg_lo:[0,0,1] neg_hi:[0,0,1]
	v_pk_fma_f32 v[32:33], v[18:19], v[6:7], v[32:33]
	v_pk_fma_f32 v[30:31], v[20:21], v[8:9], v[30:31]
	v_lshl_add_u64 v[4:5], v[4:5], 0, v[218:219]
	v_cndmask_b32_e64 v159, v21, v27, s[4:5]
	v_cndmask_b32_e64 v158, v20, v26, s[4:5]
	v_cndmask_b32_e64 v161, v19, v29, s[4:5]
	v_cndmask_b32_e64 v160, v18, v28, s[4:5]
	v_cndmask_b32_e64 v155, v25, v31, s[4:5]
	v_cndmask_b32_e64 v154, v24, v30, s[4:5]
	v_cndmask_b32_e64 v157, v23, v33, s[4:5]
	v_cndmask_b32_e64 v156, v22, v32, s[4:5]
	v_cvt_pk_bf16_f32 v18, v160, v161
	v_cvt_pk_bf16_f32 v19, v158, v159
	v_cvt_pk_bf16_f32 v20, v156, v157
	v_cvt_pk_bf16_f32 v21, v154, v155
	s_nop 1
	v_permlane16_swap_b32_e32 v18, v20
	v_permlane16_swap_b32_e32 v19, v21
	global_store_dwordx4 v[4:5], v[18:21], off
	s_nop 1
	v_cvt_f32_i32_e32 v19, v151
	v_cvt_f32_i32_e32 v18, v150
	v_cvt_f32_i32_e32 v21, v153
	v_cvt_f32_i32_e32 v20, v152
	v_cvt_f32_i32_e32 v23, v147
	v_cvt_f32_i32_e32 v25, v149
	v_cvt_f32_i32_e32 v24, v148
	v_cvt_f32_i32_e32 v22, v146
	v_add_u32_e32 v3, s35, v190
	v_mad_u64_u32 v[4:5], s[8:9], v3, 48, s[52:53]
	v_pk_mul_f32 v[20:21], v[2:3], v[20:21] op_sel_hi:[0,1]
	v_pk_mul_f32 v[18:19], v[2:3], v[18:19] op_sel_hi:[0,1]
	v_pk_mul_f32 v[24:25], v[2:3], v[24:25] op_sel_hi:[0,1]
	v_pk_mul_f32 v[2:3], v[2:3], v[22:23] op_sel_hi:[0,1]
	v_pk_mul_f32 v[2:3], v[98:99], v[2:3]
	v_pk_mul_f32 v[18:19], v[102:103], v[18:19]
	v_pk_mul_f32 v[30:31], v[2:3], v[186:187]
	v_pk_mul_f32 v[22:23], v[100:101], v[24:25]
	v_pk_mul_f32 v[26:27], v[2:3], v[6:7]
	v_pk_fma_f32 v[6:7], v[18:19], v[6:7], v[30:31]
	v_pk_mul_f32 v[20:21], v[104:105], v[20:21]
	v_pk_mul_f32 v[28:29], v[22:23], v[188:189]
	v_cndmask_b32_e64 v149, v3, v7, s[4:5]
	s_waitcnt lgkmcnt(1)
	v_fmamk_f32 v3, v244, 0x39800000, v237
	v_pk_mul_f32 v[24:25], v[22:23], v[8:9]
	v_pk_fma_f32 v[8:9], v[20:21], v[8:9], v[28:29]
	v_cndmask_b32_e64 v148, v2, v6, s[4:5]
	v_mul_f32_e32 v6, 0x4f800000, v3
	v_cmp_gt_f32_e32 vcc, s73, v3
	v_cndmask_b32_e64 v146, v22, v8, s[4:5]
	v_cndmask_b32_e64 v147, v23, v9, s[4:5]
	v_cndmask_b32_e32 v8, v3, v6, vcc
	v_sqrt_f32_e32 v9, v8
	v_pk_fma_f32 v[26:27], v[18:19], v[186:187], v[26:27] neg_lo:[0,0,1] neg_hi:[0,0,1]
	v_ashrrev_i32_e32 v5, 31, v4
	v_cndmask_b32_e64 v152, v18, v26, s[4:5]
	v_add_u32_e32 v18, -1, v9
	v_cndmask_b32_e64 v153, v19, v27, s[4:5]
	v_fma_f32 v19, -v18, v9, v8
	v_cmp_ge_f32_e64 s[8:9], 0, v19
	v_add_u32_e32 v19, 1, v9
	v_lshlrev_b64 v[4:5], 20, v[4:5]
	v_cndmask_b32_e64 v18, v9, v18, s[8:9]
	v_fma_f32 v9, -v19, v9, v8
	v_cmp_lt_f32_e64 s[8:9], 0, v9
	v_lshl_add_u64 v[4:5], s[16:17], 0, v[4:5]
	v_lshl_add_u64 v[4:5], v[4:5], 0, v[194:195]
	v_cndmask_b32_e64 v9, v18, v19, s[8:9]
	v_mul_f32_e32 v18, 0x37800000, v9
	v_cndmask_b32_e32 v9, v9, v18, vcc
	v_cmp_class_f32_e32 vcc, v8, v238
	v_lshl_add_u64 v[4:5], v[4:5], 0, s[26:27]
	v_pk_fma_f32 v[24:25], v[20:21], v[188:189], v[24:25] neg_lo:[0,0,1] neg_hi:[0,0,1]
	v_cndmask_b32_e32 v8, v9, v8, vcc
	v_div_scale_f32 v9, s[8:9], v8, v8, v225
	v_rcp_f32_e32 v18, v9
	v_lshl_add_u64 v[4:5], v[4:5], 0, v[218:219]
	v_cndmask_b32_e64 v151, v21, v25, s[4:5]
	v_cndmask_b32_e64 v150, v20, v24, s[4:5]
	v_cvt_pk_bf16_f32 v250, v152, v153
	v_cvt_pk_bf16_f32 v251, v150, v151
	v_cvt_pk_bf16_f32 v252, v148, v149
	v_cvt_pk_bf16_f32 v253, v146, v147
	s_nop 1
	v_permlane16_swap_b32_e32 v250, v252
	v_permlane16_swap_b32_e32 v251, v253
	global_store_dwordx4 v[4:5], v[250:253], off
	s_nop 1
	v_fma_f32 v2, -v9, v18, 1.0
	v_fmac_f32_e32 v18, v2, v18
	v_div_scale_f32 v2, vcc, v225, v8, v225
	v_mul_f32_e32 v4, v2, v18
	v_fma_f32 v5, -v9, v4, v2
	v_fmac_f32_e32 v4, v5, v18
	v_add_u32_e32 v3, 32, v216
	v_fma_f32 v2, -v9, v4, v2
	v_div_fmas_f32 v2, v2, v18, v4
	v_ashrrev_i32_e32 v30, 12, v3
	v_cvt_f32_i32_e32 v19, v139
	v_cvt_f32_i32_e32 v21, v141
	v_cvt_f32_i32_e32 v20, v140
	v_cvt_f32_i32_e32 v18, v138
	v_div_fixup_f32 v2, v2, v8, v225
	v_add_u32_e32 v4, s31, v30
	v_cvt_f32_i32_e32 v7, v143
	v_cvt_f32_i32_e32 v6, v142
	v_cvt_f32_i32_e32 v9, v145
	v_cvt_f32_i32_e32 v8, v144
	v_mad_u64_u32 v[4:5], s[8:9], v4, 48, s[18:19]
	v_ashrrev_i32_e32 v5, 31, v4
	v_lshlrev_b32_e32 v3, 8, v3
	v_lshlrev_b64 v[4:5], 20, v[4:5]
	v_pk_mul_f32 v[20:21], v[2:3], v[20:21] op_sel_hi:[0,1]
	v_pk_mul_f32 v[18:19], v[2:3], v[18:19] op_sel_hi:[0,1]
	v_lshl_add_u64 v[4:5], s[16:17], 0, v[4:5]
	v_and_b32_e32 v194, 0xfff00, v3
	v_pk_mul_f32 v[8:9], v[2:3], v[8:9] op_sel_hi:[0,1]
	v_pk_mul_f32 v[6:7], v[2:3], v[6:7] op_sel_hi:[0,1]
	v_pk_mul_f32 v[18:19], v[106:107], v[18:19]
	v_pk_mul_f32 v[20:21], v[108:109], v[20:21]
	v_lshl_add_u64 v[4:5], v[4:5], 0, v[194:195]
	v_pk_mul_f32 v[6:7], v[110:111], v[6:7]
	v_pk_mul_f32 v[8:9], v[112:113], v[8:9]
	v_pk_mul_f32 v[22:23], v[20:21], v[12:13]
	v_pk_mul_f32 v[24:25], v[18:19], v[10:11]
	s_waitcnt vmcnt(8)
	v_pk_mul_f32 v[26:27], v[20:21], v[184:185]
	v_pk_mul_f32 v[28:29], v[18:19], v[182:183]
	v_lshl_add_u64 v[4:5], v[4:5], 0, s[26:27]
	v_pk_fma_f32 v[24:25], v[6:7], v[182:183], v[24:25] neg_lo:[0,0,1] neg_hi:[0,0,1]
	v_pk_fma_f32 v[22:23], v[8:9], v[184:185], v[22:23] neg_lo:[0,0,1] neg_hi:[0,0,1]
	v_pk_fma_f32 v[28:29], v[6:7], v[10:11], v[28:29]
	v_pk_fma_f32 v[26:27], v[8:9], v[12:13], v[26:27]
	v_lshl_add_u64 v[4:5], v[4:5], 0, v[218:219]
	v_cndmask_b32_e64 v143, v9, v23, s[4:5]
	v_cndmask_b32_e64 v142, v8, v22, s[4:5]
	v_cndmask_b32_e64 v145, v7, v25, s[4:5]
	v_cndmask_b32_e64 v144, v6, v24, s[4:5]
	v_cndmask_b32_e64 v139, v21, v27, s[4:5]
	v_cndmask_b32_e64 v138, v20, v26, s[4:5]
	v_cndmask_b32_e64 v141, v19, v29, s[4:5]
	v_cndmask_b32_e64 v140, v18, v28, s[4:5]
	v_cvt_pk_bf16_f32 v6, v144, v145
	v_cvt_pk_bf16_f32 v7, v142, v143
	v_cvt_pk_bf16_f32 v8, v140, v141
	v_cvt_pk_bf16_f32 v9, v138, v139
	s_nop 1
	v_permlane16_swap_b32_e32 v6, v8
	v_permlane16_swap_b32_e32 v7, v9
	global_store_dwordx4 v[4:5], v[6:9], off
	s_nop 1
	v_cvt_f32_i32_e32 v7, v135
	v_cvt_f32_i32_e32 v6, v134
	v_cvt_f32_i32_e32 v9, v137
	v_cvt_f32_i32_e32 v8, v136
	v_cvt_f32_i32_e32 v19, v131
	v_cvt_f32_i32_e32 v21, v133
	v_cvt_f32_i32_e32 v20, v132
	v_cvt_f32_i32_e32 v18, v130
	v_add_u32_e32 v3, s35, v30
	v_mad_u64_u32 v[4:5], s[8:9], v3, 48, s[52:53]
	v_pk_mul_f32 v[8:9], v[2:3], v[8:9] op_sel_hi:[0,1]
	v_pk_mul_f32 v[6:7], v[2:3], v[6:7] op_sel_hi:[0,1]
	v_pk_mul_f32 v[20:21], v[2:3], v[20:21] op_sel_hi:[0,1]
	v_pk_mul_f32 v[2:3], v[2:3], v[18:19] op_sel_hi:[0,1]
	v_pk_mul_f32 v[2:3], v[98:99], v[2:3]
	v_pk_mul_f32 v[6:7], v[102:103], v[6:7]
	v_pk_mul_f32 v[26:27], v[2:3], v[182:183]
	v_pk_mul_f32 v[22:23], v[2:3], v[10:11]
	v_pk_fma_f32 v[10:11], v[6:7], v[10:11], v[26:27]
	v_pk_mul_f32 v[18:19], v[100:101], v[20:21]
	v_cndmask_b32_e64 v132, v2, v10, s[4:5]
	s_waitcnt lgkmcnt(0)
	v_fmamk_f32 v2, v243, 0x39800000, v237
	v_pk_mul_f32 v[8:9], v[104:105], v[8:9]
	v_pk_mul_f32 v[20:21], v[18:19], v[12:13]
	v_pk_fma_f32 v[22:23], v[6:7], v[182:183], v[22:23] neg_lo:[0,0,1] neg_hi:[0,0,1]
	v_cndmask_b32_e64 v133, v3, v11, s[4:5]
	v_mul_f32_e32 v3, 0x4f800000, v2
	v_cmp_gt_f32_e32 vcc, s73, v2
	v_pk_fma_f32 v[20:21], v[8:9], v[184:185], v[20:21] neg_lo:[0,0,1] neg_hi:[0,0,1]
	v_pk_mul_f32 v[24:25], v[18:19], v[184:185]
	v_cndmask_b32_e64 v137, v7, v23, s[4:5]
	v_cndmask_b32_e32 v7, v2, v3, vcc
	v_pk_fma_f32 v[12:13], v[8:9], v[12:13], v[24:25]
	v_cndmask_b32_e64 v134, v8, v20, s[4:5]
	v_sqrt_f32_e32 v8, v7
	v_cndmask_b32_e64 v135, v9, v21, s[4:5]
	v_ashrrev_i32_e32 v5, 31, v4
	v_lshlrev_b64 v[4:5], 20, v[4:5]
	v_add_u32_e32 v9, -1, v8
	v_fma_f32 v10, -v9, v8, v7
	v_cmp_ge_f32_e64 s[8:9], 0, v10
	v_add_u32_e32 v10, 1, v8
	v_lshl_add_u64 v[4:5], s[16:17], 0, v[4:5]
	v_cndmask_b32_e64 v9, v8, v9, s[8:9]
	v_fma_f32 v8, -v10, v8, v7
	v_cmp_lt_f32_e64 s[8:9], 0, v8
	v_lshl_add_u64 v[4:5], v[4:5], 0, v[194:195]
	v_lshl_add_u64 v[4:5], v[4:5], 0, s[26:27]
	v_cndmask_b32_e64 v8, v9, v10, s[8:9]
	v_mul_f32_e32 v9, 0x37800000, v8
	v_cndmask_b32_e32 v8, v8, v9, vcc
	v_cmp_class_f32_e32 vcc, v7, v238
	v_lshl_add_u64 v[4:5], v[4:5], 0, v[218:219]
	v_cndmask_b32_e64 v136, v6, v22, s[4:5]
	v_cndmask_b32_e32 v8, v8, v7, vcc
	v_div_scale_f32 v9, s[8:9], v8, v8, v242
	v_rcp_f32_e32 v10, v9
	v_cvt_pk_bf16_f32 v250, v136, v137
	v_cvt_pk_bf16_f32 v251, v134, v135
	v_cndmask_b32_e64 v131, v19, v13, s[4:5]
	v_cndmask_b32_e64 v130, v18, v12, s[4:5]
	v_cvt_pk_bf16_f32 v252, v132, v133
	v_cvt_pk_bf16_f32 v253, v130, v131
	s_nop 1
	v_permlane16_swap_b32_e32 v250, v252
	v_permlane16_swap_b32_e32 v251, v253
	global_store_dwordx4 v[4:5], v[250:253], off
	s_nop 1
	v_fma_f32 v2, -v9, v10, 1.0
	v_fmac_f32_e32 v10, v2, v10
	v_div_scale_f32 v2, vcc, v242, v8, v242
	v_mul_f32_e32 v3, v2, v10
	v_fma_f32 v4, -v9, v3, v2
	v_fmac_f32_e32 v3, v4, v10
	v_fma_f32 v2, -v9, v3, v2
	v_div_fmas_f32 v2, v2, v10, v3
	v_ashrrev_i32_e32 v3, 12, v226
	v_lshlrev_b32_e32 v6, 8, v226
	v_cvt_f32_i32_e32 v11, v123
	v_cvt_f32_i32_e32 v13, v125
	v_cvt_f32_i32_e32 v12, v124
	v_cvt_f32_i32_e32 v10, v122
	v_div_fixup_f32 v2, v2, v8, v242
	v_add_u32_e32 v4, s31, v3
	v_and_b32_e32 v194, 0xfff00, v6
	v_cvt_f32_i32_e32 v7, v127
	v_cvt_f32_i32_e32 v6, v126
	v_cvt_f32_i32_e32 v9, v129
	v_cvt_f32_i32_e32 v8, v128
	v_mad_u64_u32 v[4:5], s[8:9], v4, 48, s[18:19]
	v_ashrrev_i32_e32 v5, 31, v4
	v_lshlrev_b64 v[4:5], 20, v[4:5]
	v_pk_mul_f32 v[12:13], v[2:3], v[12:13] op_sel_hi:[0,1]
	v_pk_mul_f32 v[10:11], v[2:3], v[10:11] op_sel_hi:[0,1]
	v_lshl_add_u64 v[4:5], s[16:17], 0, v[4:5]
	v_pk_mul_f32 v[8:9], v[2:3], v[8:9] op_sel_hi:[0,1]
	v_pk_mul_f32 v[6:7], v[2:3], v[6:7] op_sel_hi:[0,1]
	v_pk_mul_f32 v[10:11], v[106:107], v[10:11]
	v_pk_mul_f32 v[12:13], v[108:109], v[12:13]
	v_lshl_add_u64 v[4:5], v[4:5], 0, v[194:195]
	v_pk_mul_f32 v[6:7], v[110:111], v[6:7]
	v_pk_mul_f32 v[8:9], v[112:113], v[8:9]
	v_pk_mul_f32 v[18:19], v[12:13], v[16:17]
	v_pk_mul_f32 v[20:21], v[10:11], v[14:15]
	v_pk_mul_f32 v[22:23], v[12:13], v[180:181]
	v_pk_mul_f32 v[24:25], v[10:11], v[178:179]
	v_lshl_add_u64 v[4:5], v[4:5], 0, s[26:27]
	v_pk_fma_f32 v[20:21], v[6:7], v[178:179], v[20:21] neg_lo:[0,0,1] neg_hi:[0,0,1]
	v_pk_fma_f32 v[18:19], v[8:9], v[180:181], v[18:19] neg_lo:[0,0,1] neg_hi:[0,0,1]
	v_pk_fma_f32 v[24:25], v[6:7], v[14:15], v[24:25]
	v_pk_fma_f32 v[22:23], v[8:9], v[16:17], v[22:23]
	v_lshl_add_u64 v[4:5], v[4:5], 0, v[218:219]
	v_cndmask_b32_e64 v127, v9, v19, s[4:5]
	v_cndmask_b32_e64 v126, v8, v18, s[4:5]
	v_cndmask_b32_e64 v129, v7, v21, s[4:5]
	v_cndmask_b32_e64 v128, v6, v20, s[4:5]
	v_cndmask_b32_e64 v123, v13, v23, s[4:5]
	v_cndmask_b32_e64 v122, v12, v22, s[4:5]
	v_cndmask_b32_e64 v125, v11, v25, s[4:5]
	v_cndmask_b32_e64 v124, v10, v24, s[4:5]
	v_cvt_pk_bf16_f32 v6, v128, v129
	v_cvt_pk_bf16_f32 v7, v126, v127
	v_cvt_pk_bf16_f32 v8, v124, v125
	v_cvt_pk_bf16_f32 v9, v122, v123
	s_nop 1
	v_permlane16_swap_b32_e32 v6, v8
	v_permlane16_swap_b32_e32 v7, v9
	global_store_dwordx4 v[4:5], v[6:9], off
	s_nop 1
	v_cvt_f32_i32_e32 v7, v119
	v_cvt_f32_i32_e32 v6, v118
	v_cvt_f32_i32_e32 v9, v121
	v_cvt_f32_i32_e32 v8, v120
	v_cvt_f32_i32_e32 v11, v115
	v_cvt_f32_i32_e32 v13, v117
	v_cvt_f32_i32_e32 v12, v116
	v_cvt_f32_i32_e32 v10, v114
	v_add_u32_e32 v3, s35, v3
	v_mad_u64_u32 v[4:5], s[8:9], v3, 48, s[52:53]
	v_ashrrev_i32_e32 v5, 31, v4
	v_lshlrev_b64 v[4:5], 20, v[4:5]
	v_pk_mul_f32 v[8:9], v[2:3], v[8:9] op_sel_hi:[0,1]
	v_pk_mul_f32 v[6:7], v[2:3], v[6:7] op_sel_hi:[0,1]
	v_pk_mul_f32 v[12:13], v[2:3], v[12:13] op_sel_hi:[0,1]
	v_pk_mul_f32 v[2:3], v[2:3], v[10:11] op_sel_hi:[0,1]
	v_lshl_add_u64 v[4:5], s[16:17], 0, v[4:5]
	v_pk_mul_f32 v[2:3], v[98:99], v[2:3]
	v_pk_mul_f32 v[10:11], v[100:101], v[12:13]
	v_lshl_add_u64 v[4:5], v[4:5], 0, v[194:195]
	v_pk_mul_f32 v[6:7], v[102:103], v[6:7]
	v_pk_mul_f32 v[8:9], v[104:105], v[8:9]
	v_pk_mul_f32 v[12:13], v[10:11], v[16:17]
	v_pk_mul_f32 v[18:19], v[2:3], v[14:15]
	v_pk_mul_f32 v[22:23], v[2:3], v[178:179]
	v_lshl_add_u64 v[4:5], v[4:5], 0, s[26:27]
	v_pk_fma_f32 v[18:19], v[6:7], v[178:179], v[18:19] neg_lo:[0,0,1] neg_hi:[0,0,1]
	v_pk_fma_f32 v[12:13], v[8:9], v[180:181], v[12:13] neg_lo:[0,0,1] neg_hi:[0,0,1]
	v_pk_mul_f32 v[20:21], v[10:11], v[180:181]
	v_pk_fma_f32 v[14:15], v[6:7], v[14:15], v[22:23]
	v_lshl_add_u64 v[4:5], v[4:5], 0, v[218:219]
	v_pk_fma_f32 v[16:17], v[8:9], v[16:17], v[20:21]
	v_cndmask_b32_e64 v119, v9, v13, s[4:5]
	v_cndmask_b32_e64 v118, v8, v12, s[4:5]
	v_cndmask_b32_e64 v121, v7, v19, s[4:5]
	v_cndmask_b32_e64 v120, v6, v18, s[4:5]
	v_cndmask_b32_e64 v117, v3, v15, s[4:5]
	v_cndmask_b32_e64 v116, v2, v14, s[4:5]
	v_cvt_pk_bf16_f32 v250, v120, v121
	v_cvt_pk_bf16_f32 v251, v118, v119
	v_cndmask_b32_e64 v115, v11, v17, s[4:5]
	v_cndmask_b32_e64 v114, v10, v16, s[4:5]
	v_cvt_pk_bf16_f32 v252, v116, v117
	v_cvt_pk_bf16_f32 v253, v114, v115
	s_nop 1
	v_permlane16_swap_b32_e32 v250, v252
	v_permlane16_swap_b32_e32 v251, v253
	global_store_dwordx4 v[4:5], v[250:253], off
	s_nop 1
	ds_read2st64_b32 v[184:185], v240 offset0:6 offset1:10
	ds_read2_b32 v[180:181], v241 offset0:144 offset1:160
	ds_read_b32 v186, v240 offset:2752
	s_and_b64 vcc, exec, s[6:7]
	v_add_u32_e32 v182, 0x80, v216
	s_cbranch_vccnz .LBB0_318
	v_ashrrev_i32_e32 v183, 31, v182
	v_lshlrev_b64 v[2:3], 6, v[182:183]
	v_lshl_add_u64 v[4:5], v[222:223], 0, v[2:3]
	v_lshl_add_u64 v[2:3], v[220:221], 0, v[2:3]
	global_load_dwordx4 v[30:33], v[4:5], off
	global_load_dwordx4 v[26:29], v[2:3], off
	s_branch .LBB0_319

.LBB0_326:
	s_waitcnt lgkmcnt(5)
	v_fmamk_f32 v179, v184, 0x39800000, v237
	v_mul_f32_e32 v184, 0x4f800000, v179
	v_cmp_gt_f32_e32 vcc, s73, v179
	s_sub_i32 s8, s40, 24
	v_cvt_f32_i32_e32 v91, v91
	v_cndmask_b32_e32 v179, v179, v184, vcc
	v_sqrt_f32_e32 v184, v179
	v_cvt_f32_i32_e32 v93, v93
	v_cvt_f32_i32_e32 v92, v92
	v_cvt_f32_i32_e32 v90, v90
	v_add_u32_e32 v189, -1, v184
	v_fma_f32 v190, -v189, v184, v179
	v_cmp_ge_f32_e64 s[6:7], 0, v190
	v_add_u32_e32 v190, 1, v184
	s_cmp_lt_u32 s8, 12
	v_cndmask_b32_e64 v189, v184, v189, s[6:7]
	v_fma_f32 v184, -v190, v184, v179
	v_cmp_lt_f32_e64 s[6:7], 0, v184
	v_cvt_f32_i32_e32 v95, v95
	v_cvt_f32_i32_e32 v94, v94
	v_cndmask_b32_e64 v184, v189, v190, s[6:7]
	v_mul_f32_e32 v189, 0x37800000, v184
	v_cndmask_b32_e32 v184, v184, v189, vcc
	v_cmp_class_f32_e32 vcc, v179, v238
	v_cvt_f32_i32_e32 v97, v97
	v_cvt_f32_i32_e32 v96, v96
	v_cndmask_b32_e32 v179, v184, v179, vcc
	v_div_scale_f32 v184, s[6:7], v179, v179, v185
	v_rcp_f32_e32 v189, v184
	s_cselect_b64 s[6:7], -1, 0
	s_cmp_gt_u32 s8, 11
	v_cvt_f32_i32_e32 v83, v83
	v_fma_f32 v190, -v184, v189, 1.0
	v_fmac_f32_e32 v189, v190, v189
	v_div_scale_f32 v190, vcc, v185, v179, v185
	v_mul_f32_e32 v191, v190, v189
	v_fma_f32 v192, -v184, v191, v190
	v_fmac_f32_e32 v191, v192, v189
	v_fma_f32 v184, -v184, v191, v190
	v_div_fmas_f32 v184, v184, v189, v191
	v_div_fixup_f32 v184, v184, v179, v185
	v_ashrrev_i32_e32 v179, 12, v182
	v_add_u32_e32 v185, s31, v179
	v_mad_u64_u32 v[190:191], s[8:9], v185, 48, s[18:19]
	v_ashrrev_i32_e32 v191, 31, v190
	v_cvt_f32_i32_e32 v82, v82
	v_lshlrev_b64 v[190:191], 20, v[190:191]
	v_lshlrev_b32_e32 v182, 8, v182
	v_pk_mul_f32 v[92:93], v[184:185], v[92:93] op_sel_hi:[0,1]
	v_pk_mul_f32 v[90:91], v[184:185], v[90:91] op_sel_hi:[0,1]
	v_cvt_f32_i32_e32 v87, v87
	v_cvt_f32_i32_e32 v86, v86
	v_cvt_f32_i32_e32 v85, v85
	v_cvt_f32_i32_e32 v84, v84
	v_lshl_add_u64 v[190:191], s[16:17], 0, v[190:191]
	v_and_b32_e32 v194, 0xfff00, v182
	v_pk_mul_f32 v[96:97], v[184:185], v[96:97] op_sel_hi:[0,1]
	v_pk_mul_f32 v[94:95], v[184:185], v[94:95] op_sel_hi:[0,1]
	v_pk_mul_f32 v[220:221], v[106:107], v[90:91]
	v_pk_mul_f32 v[90:91], v[108:109], v[92:93]
	v_cvt_f32_i32_e32 v89, v89
	v_cvt_f32_i32_e32 v88, v88
	v_lshl_add_u64 v[190:191], v[190:191], 0, v[194:195]
	v_pk_mul_f32 v[192:193], v[110:111], v[94:95]
	v_pk_mul_f32 v[94:95], v[112:113], v[96:97]
	s_waitcnt vmcnt(0)
	v_pk_mul_f32 v[92:93], v[90:91], v[28:29]
	v_pk_mul_f32 v[96:97], v[220:221], v[26:27]
	v_lshl_add_u64 v[190:191], v[190:191], 0, s[26:27]
	v_pk_fma_f32 v[96:97], v[192:193], v[30:31], v[96:97] neg_lo:[0,0,1] neg_hi:[0,0,1]
	v_pk_fma_f32 v[92:93], v[94:95], v[32:33], v[92:93] neg_lo:[0,0,1] neg_hi:[0,0,1]
	v_pk_mul_f32 v[222:223], v[90:91], v[32:33]
	v_pk_mul_f32 v[224:225], v[220:221], v[30:31]
	v_pk_mul_f32 v[82:83], v[184:185], v[82:83] op_sel_hi:[0,1]
	v_lshl_add_u64 v[190:191], v[190:191], 0, v[218:219]
	v_pk_fma_f32 v[224:225], v[192:193], v[26:27], v[224:225]
	v_pk_fma_f32 v[222:223], v[94:95], v[28:29], v[222:223]
	v_cndmask_b32_e64 v95, v95, v93, s[4:5]
	v_cndmask_b32_e64 v94, v94, v92, s[4:5]
	v_cndmask_b32_e64 v97, v193, v97, s[4:5]
	v_cndmask_b32_e64 v96, v192, v96, s[4:5]
	v_cvt_pk_bf16_f32 v250, v96, v97
	v_cvt_pk_bf16_f32 v251, v94, v95
	v_pk_mul_f32 v[86:87], v[184:185], v[86:87] op_sel_hi:[0,1]
	v_pk_mul_f32 v[84:85], v[184:185], v[84:85] op_sel_hi:[0,1]
	v_pk_mul_f32 v[82:83], v[98:99], v[82:83]
	v_cndmask_b32_e64 v91, v91, v223, s[4:5]
	v_cndmask_b32_e64 v90, v90, v222, s[4:5]
	v_cndmask_b32_e64 v93, v221, v225, s[4:5]
	v_cndmask_b32_e64 v92, v220, v224, s[4:5]
	v_cvt_pk_bf16_f32 v252, v92, v93
	v_cvt_pk_bf16_f32 v253, v90, v91
	s_nop 1
	v_permlane16_swap_b32_e32 v250, v252
	v_permlane16_swap_b32_e32 v251, v253
	global_store_dwordx4 v[190:191], v[250:253], off
	s_nop 1
	v_pk_mul_f32 v[88:89], v[184:185], v[88:89] op_sel_hi:[0,1]
	v_pk_mul_f32 v[86:87], v[102:103], v[86:87]
	v_pk_mul_f32 v[84:85], v[100:101], v[84:85]
	v_pk_mul_f32 v[192:193], v[82:83], v[26:27]
	v_pk_mul_f32 v[88:89], v[104:105], v[88:89]
	v_pk_mul_f32 v[184:185], v[84:85], v[28:29]
	v_pk_fma_f32 v[192:193], v[86:87], v[30:31], v[192:193] neg_lo:[0,0,1] neg_hi:[0,0,1]
	v_pk_mul_f32 v[30:31], v[82:83], v[30:31]
	v_pk_fma_f32 v[184:185], v[88:89], v[32:33], v[184:185] neg_lo:[0,0,1] neg_hi:[0,0,1]
	v_pk_mul_f32 v[32:33], v[84:85], v[32:33]
	v_pk_fma_f32 v[220:221], v[86:87], v[26:27], v[30:31]
	v_pk_fma_f32 v[26:27], v[88:89], v[28:29], v[32:33]
	v_cndmask_b32_e64 v29, v83, v221, s[4:5]
	s_waitcnt lgkmcnt(2)
	v_fmamk_f32 v83, v188, 0x39800000, v237
	v_cndmask_b32_e64 v26, v84, v26, s[4:5]
	v_mul_f32_e32 v84, 0x4f800000, v83
	v_cmp_gt_f32_e32 vcc, s73, v83
	v_cndmask_b32_e64 v32, v86, v192, s[4:5]
	v_cndmask_b32_e64 v33, v87, v193, s[4:5]
	v_cndmask_b32_e32 v86, v83, v84, vcc
	v_sqrt_f32_e32 v87, v86
	v_add_u32_e32 v179, s35, v179
	v_cndmask_b32_e64 v30, v88, v184, s[4:5]
	v_mad_u64_u32 v[190:191], s[8:9], v179, 48, s[52:53]
	v_add_u32_e32 v88, -1, v87
	v_cndmask_b32_e64 v31, v89, v185, s[4:5]
	v_fma_f32 v89, -v88, v87, v86
	v_cmp_ge_f32_e64 s[8:9], 0, v89
	v_add_u32_e32 v89, 1, v87
	v_ashrrev_i32_e32 v191, 31, v190
	v_cndmask_b32_e64 v88, v87, v88, s[8:9]
	v_fma_f32 v87, -v89, v87, v86
	v_cmp_lt_f32_e64 s[8:9], 0, v87
	v_lshlrev_b64 v[190:191], 20, v[190:191]
	v_lshl_add_u64 v[190:191], s[16:17], 0, v[190:191]
	v_cndmask_b32_e64 v87, v88, v89, s[8:9]
	v_mul_f32_e32 v88, 0x37800000, v87
	v_cndmask_b32_e32 v87, v87, v88, vcc
	v_cmp_class_f32_e32 vcc, v86, v238
	v_lshl_add_u64 v[190:191], v[190:191], 0, v[194:195]
	v_lshl_add_u64 v[190:191], v[190:191], 0, s[26:27]
	v_cndmask_b32_e32 v86, v87, v86, vcc
	v_div_scale_f32 v87, s[8:9], v86, v86, v180
	v_rcp_f32_e32 v88, v87
	v_lshl_add_u64 v[190:191], v[190:191], 0, v[218:219]
	v_cndmask_b32_e64 v28, v82, v220, s[4:5]
	v_cvt_pk_bf16_f32 v82, v32, v33
	v_cvt_pk_bf16_f32 v83, v30, v31
	v_cndmask_b32_e64 v27, v85, v27, s[4:5]
	v_cvt_pk_bf16_f32 v84, v28, v29
	v_cvt_pk_bf16_f32 v85, v26, v27
	s_nop 1
	v_permlane16_swap_b32_e32 v82, v84
	v_permlane16_swap_b32_e32 v83, v85
	global_store_dwordx4 v[190:191], v[82:85], off
	s_nop 1
	v_fma_f32 v82, -v87, v88, 1.0
	v_fmac_f32_e32 v88, v82, v88
	v_div_scale_f32 v82, vcc, v180, v86, v180
	v_mul_f32_e32 v84, v82, v88
	v_fma_f32 v85, -v87, v84, v82
	v_add_u32_e32 v83, 0x90, v216
	v_fmac_f32_e32 v84, v85, v88
	v_fma_f32 v82, -v87, v84, v82
	v_ashrrev_i32_e32 v179, 12, v83
	v_cvt_f32_i32_e32 v75, v75
	v_cvt_f32_i32_e32 v77, v77
	v_cvt_f32_i32_e32 v76, v76
	v_cvt_f32_i32_e32 v74, v74
	v_div_fmas_f32 v82, v82, v88, v84
	v_add_u32_e32 v84, s31, v179
	v_cvt_f32_i32_e32 v79, v79
	v_cvt_f32_i32_e32 v78, v78
	v_cvt_f32_i32_e32 v81, v81
	v_cvt_f32_i32_e32 v80, v80
	v_mad_u64_u32 v[84:85], s[8:9], v84, 48, s[18:19]
	v_div_fixup_f32 v82, v82, v86, v180
	v_ashrrev_i32_e32 v85, 31, v84
	v_lshlrev_b32_e32 v83, 8, v83
	v_cvt_f32_i32_e32 v67, v67
	v_cvt_f32_i32_e32 v66, v66
	v_lshlrev_b64 v[84:85], 20, v[84:85]
	v_pk_mul_f32 v[76:77], v[82:83], v[76:77] op_sel_hi:[0,1]
	v_pk_mul_f32 v[74:75], v[82:83], v[74:75] op_sel_hi:[0,1]
	v_cvt_f32_i32_e32 v71, v71
	v_cvt_f32_i32_e32 v70, v70
	v_cvt_f32_i32_e32 v69, v69
	v_cvt_f32_i32_e32 v68, v68
	v_lshl_add_u64 v[84:85], s[16:17], 0, v[84:85]
	v_and_b32_e32 v194, 0xfff00, v83
	v_pk_mul_f32 v[80:81], v[82:83], v[80:81] op_sel_hi:[0,1]
	v_pk_mul_f32 v[78:79], v[82:83], v[78:79] op_sel_hi:[0,1]
	v_pk_mul_f32 v[88:89], v[106:107], v[74:75]
	v_pk_mul_f32 v[74:75], v[108:109], v[76:77]
	v_cvt_f32_i32_e32 v73, v73
	v_cvt_f32_i32_e32 v72, v72
	v_lshl_add_u64 v[84:85], v[84:85], 0, v[194:195]
	v_pk_mul_f32 v[86:87], v[110:111], v[78:79]
	v_pk_mul_f32 v[78:79], v[112:113], v[80:81]
	v_pk_mul_f32 v[76:77], v[74:75], v[20:21]
	v_pk_mul_f32 v[80:81], v[88:89], v[18:19]
	v_add_u32_e32 v83, s35, v179
	v_lshl_add_u64 v[84:85], v[84:85], 0, s[26:27]
	v_pk_fma_f32 v[80:81], v[86:87], v[22:23], v[80:81] neg_lo:[0,0,1] neg_hi:[0,0,1]
	v_pk_fma_f32 v[76:77], v[78:79], v[24:25], v[76:77] neg_lo:[0,0,1] neg_hi:[0,0,1]
	v_pk_mul_f32 v[184:185], v[74:75], v[24:25]
	v_pk_mul_f32 v[188:189], v[88:89], v[22:23]
	v_pk_mul_f32 v[66:67], v[82:83], v[66:67] op_sel_hi:[0,1]
	v_lshl_add_u64 v[84:85], v[84:85], 0, v[218:219]
	v_pk_fma_f32 v[188:189], v[86:87], v[18:19], v[188:189]
	v_pk_fma_f32 v[184:185], v[78:79], v[20:21], v[184:185]
	v_cndmask_b32_e64 v79, v79, v77, s[4:5]
	v_cndmask_b32_e64 v78, v78, v76, s[4:5]
	v_cndmask_b32_e64 v81, v87, v81, s[4:5]
	v_cndmask_b32_e64 v80, v86, v80, s[4:5]
	v_cvt_pk_bf16_f32 v86, v80, v81
	v_cvt_pk_bf16_f32 v87, v78, v79
	v_pk_mul_f32 v[70:71], v[82:83], v[70:71] op_sel_hi:[0,1]
	v_pk_mul_f32 v[68:69], v[82:83], v[68:69] op_sel_hi:[0,1]
	v_pk_mul_f32 v[66:67], v[98:99], v[66:67]
	v_cndmask_b32_e64 v75, v75, v185, s[4:5]
	v_cndmask_b32_e64 v74, v74, v184, s[4:5]
	v_cndmask_b32_e64 v77, v89, v189, s[4:5]
	v_cndmask_b32_e64 v76, v88, v188, s[4:5]
	v_cvt_pk_bf16_f32 v88, v76, v77
	v_cvt_pk_bf16_f32 v89, v74, v75
	s_nop 1
	v_permlane16_swap_b32_e32 v86, v88
	v_permlane16_swap_b32_e32 v87, v89
	global_store_dwordx4 v[84:85], v[86:89], off
	s_nop 1
	v_pk_mul_f32 v[72:73], v[82:83], v[72:73] op_sel_hi:[0,1]
	v_pk_mul_f32 v[70:71], v[102:103], v[70:71]
	v_pk_mul_f32 v[68:69], v[100:101], v[68:69]
	v_pk_mul_f32 v[86:87], v[66:67], v[18:19]
	v_mad_u64_u32 v[84:85], s[8:9], v83, 48, s[52:53]
	v_pk_mul_f32 v[72:73], v[104:105], v[72:73]
	v_pk_mul_f32 v[82:83], v[68:69], v[20:21]
	v_pk_fma_f32 v[86:87], v[70:71], v[22:23], v[86:87] neg_lo:[0,0,1] neg_hi:[0,0,1]
	v_pk_mul_f32 v[22:23], v[66:67], v[22:23]
	v_pk_fma_f32 v[82:83], v[72:73], v[24:25], v[82:83] neg_lo:[0,0,1] neg_hi:[0,0,1]
	v_pk_mul_f32 v[24:25], v[68:69], v[24:25]
	v_pk_fma_f32 v[88:89], v[70:71], v[18:19], v[22:23]
	v_pk_fma_f32 v[18:19], v[72:73], v[20:21], v[24:25]
	v_cndmask_b32_e64 v21, v67, v89, s[4:5]
	s_waitcnt lgkmcnt(1)
	v_fmamk_f32 v67, v187, 0x39800000, v237
	v_cndmask_b32_e64 v18, v68, v18, s[4:5]
	v_mul_f32_e32 v68, 0x4f800000, v67
	v_cmp_gt_f32_e32 vcc, s73, v67
	v_cndmask_b32_e64 v24, v70, v86, s[4:5]
	v_cndmask_b32_e64 v25, v71, v87, s[4:5]
	v_cndmask_b32_e32 v70, v67, v68, vcc
	v_sqrt_f32_e32 v71, v70
	v_cndmask_b32_e64 v22, v72, v82, s[4:5]
	v_cndmask_b32_e64 v23, v73, v83, s[4:5]
	v_ashrrev_i32_e32 v85, 31, v84
	v_add_u32_e32 v72, -1, v71
	v_fma_f32 v73, -v72, v71, v70
	v_cmp_ge_f32_e64 s[8:9], 0, v73
	v_add_u32_e32 v73, 1, v71
	v_lshlrev_b64 v[84:85], 20, v[84:85]
	v_cndmask_b32_e64 v72, v71, v72, s[8:9]
	v_fma_f32 v71, -v73, v71, v70
	v_cmp_lt_f32_e64 s[8:9], 0, v71
	v_lshl_add_u64 v[84:85], s[16:17], 0, v[84:85]
	v_lshl_add_u64 v[84:85], v[84:85], 0, v[194:195]
	v_cndmask_b32_e64 v71, v72, v73, s[8:9]
	v_mul_f32_e32 v72, 0x37800000, v71
	v_cndmask_b32_e32 v71, v71, v72, vcc
	v_cmp_class_f32_e32 vcc, v70, v238
	v_lshl_add_u64 v[84:85], v[84:85], 0, s[26:27]
	v_lshl_add_u64 v[84:85], v[84:85], 0, v[218:219]
	v_cndmask_b32_e32 v70, v71, v70, vcc
	v_div_scale_f32 v71, s[8:9], v70, v70, v181
	v_rcp_f32_e32 v72, v71
	v_cndmask_b32_e64 v20, v66, v88, s[4:5]
	v_cvt_pk_bf16_f32 v66, v24, v25
	v_cvt_pk_bf16_f32 v67, v22, v23
	v_cndmask_b32_e64 v19, v69, v19, s[4:5]
	v_cvt_pk_bf16_f32 v68, v20, v21
	v_cvt_pk_bf16_f32 v69, v18, v19
	s_nop 1
	v_permlane16_swap_b32_e32 v66, v68
	v_permlane16_swap_b32_e32 v67, v69
	global_store_dwordx4 v[84:85], v[66:69], off
	s_nop 1
	v_fma_f32 v66, -v71, v72, 1.0
	v_fmac_f32_e32 v72, v66, v72
	v_div_scale_f32 v66, vcc, v181, v70, v181
	v_mul_f32_e32 v68, v66, v72
	v_fma_f32 v69, -v71, v68, v66
	v_add_u32_e32 v67, 0xa0, v216
	v_fmac_f32_e32 v68, v69, v72
	v_fma_f32 v66, -v71, v68, v66
	v_ashrrev_i32_e32 v86, 12, v67
	v_cvt_f32_i32_e32 v59, v59
	v_cvt_f32_i32_e32 v61, v61
	v_cvt_f32_i32_e32 v60, v60
	v_cvt_f32_i32_e32 v58, v58
	v_div_fmas_f32 v66, v66, v72, v68
	v_add_u32_e32 v68, s31, v86
	v_cvt_f32_i32_e32 v63, v63
	v_cvt_f32_i32_e32 v62, v62
	v_cvt_f32_i32_e32 v65, v65
	v_cvt_f32_i32_e32 v64, v64
	v_mad_u64_u32 v[68:69], s[8:9], v68, 48, s[18:19]
	v_div_fixup_f32 v66, v66, v70, v181
	v_ashrrev_i32_e32 v69, 31, v68
	v_lshlrev_b32_e32 v67, 8, v67
	v_cvt_f32_i32_e32 v51, v51
	v_cvt_f32_i32_e32 v50, v50
	v_lshlrev_b64 v[68:69], 20, v[68:69]
	v_pk_mul_f32 v[60:61], v[66:67], v[60:61] op_sel_hi:[0,1]
	v_pk_mul_f32 v[58:59], v[66:67], v[58:59] op_sel_hi:[0,1]
	v_cvt_f32_i32_e32 v55, v55
	v_cvt_f32_i32_e32 v54, v54
	v_cvt_f32_i32_e32 v53, v53
	v_cvt_f32_i32_e32 v52, v52
	v_lshl_add_u64 v[68:69], s[16:17], 0, v[68:69]
	v_and_b32_e32 v194, 0xfff00, v67
	v_pk_mul_f32 v[64:65], v[66:67], v[64:65] op_sel_hi:[0,1]
	v_pk_mul_f32 v[62:63], v[66:67], v[62:63] op_sel_hi:[0,1]
	v_pk_mul_f32 v[72:73], v[106:107], v[58:59]
	v_pk_mul_f32 v[58:59], v[108:109], v[60:61]
	v_cvt_f32_i32_e32 v57, v57
	v_cvt_f32_i32_e32 v56, v56
	v_lshl_add_u64 v[68:69], v[68:69], 0, v[194:195]
	v_pk_mul_f32 v[70:71], v[110:111], v[62:63]
	v_pk_mul_f32 v[62:63], v[112:113], v[64:65]
	v_pk_mul_f32 v[60:61], v[58:59], v[12:13]
	v_pk_mul_f32 v[64:65], v[72:73], v[10:11]
	v_add_u32_e32 v67, s35, v86
	v_lshl_add_u64 v[68:69], v[68:69], 0, s[26:27]
	v_pk_fma_f32 v[64:65], v[70:71], v[14:15], v[64:65] neg_lo:[0,0,1] neg_hi:[0,0,1]
	v_pk_fma_f32 v[60:61], v[62:63], v[16:17], v[60:61] neg_lo:[0,0,1] neg_hi:[0,0,1]
	v_pk_mul_f32 v[82:83], v[58:59], v[16:17]
	v_pk_mul_f32 v[84:85], v[72:73], v[14:15]
	v_pk_mul_f32 v[50:51], v[66:67], v[50:51] op_sel_hi:[0,1]
	v_lshl_add_u64 v[68:69], v[68:69], 0, v[218:219]
	v_pk_fma_f32 v[84:85], v[70:71], v[10:11], v[84:85]
	v_pk_fma_f32 v[82:83], v[62:63], v[12:13], v[82:83]
	v_cndmask_b32_e64 v63, v63, v61, s[4:5]
	v_cndmask_b32_e64 v62, v62, v60, s[4:5]
	v_cndmask_b32_e64 v65, v71, v65, s[4:5]
	v_cndmask_b32_e64 v64, v70, v64, s[4:5]
	v_cvt_pk_bf16_f32 v70, v64, v65
	v_cvt_pk_bf16_f32 v71, v62, v63
	v_pk_mul_f32 v[54:55], v[66:67], v[54:55] op_sel_hi:[0,1]
	v_pk_mul_f32 v[52:53], v[66:67], v[52:53] op_sel_hi:[0,1]
	v_pk_mul_f32 v[50:51], v[98:99], v[50:51]
	v_cndmask_b32_e64 v59, v59, v83, s[4:5]
	v_cndmask_b32_e64 v58, v58, v82, s[4:5]
	v_cndmask_b32_e64 v61, v73, v85, s[4:5]
	v_cndmask_b32_e64 v60, v72, v84, s[4:5]
	v_cvt_pk_bf16_f32 v72, v60, v61
	v_cvt_pk_bf16_f32 v73, v58, v59
	s_nop 1
	v_permlane16_swap_b32_e32 v70, v72
	v_permlane16_swap_b32_e32 v71, v73
	global_store_dwordx4 v[68:69], v[70:73], off
	s_nop 1
	v_pk_mul_f32 v[56:57], v[66:67], v[56:57] op_sel_hi:[0,1]
	v_pk_mul_f32 v[54:55], v[102:103], v[54:55]
	v_pk_mul_f32 v[52:53], v[100:101], v[52:53]
	v_pk_mul_f32 v[70:71], v[50:51], v[10:11]
	v_mad_u64_u32 v[68:69], s[8:9], v67, 48, s[52:53]
	v_pk_mul_f32 v[56:57], v[104:105], v[56:57]
	v_pk_mul_f32 v[66:67], v[52:53], v[12:13]
	v_pk_fma_f32 v[70:71], v[54:55], v[14:15], v[70:71] neg_lo:[0,0,1] neg_hi:[0,0,1]
	v_pk_mul_f32 v[14:15], v[50:51], v[14:15]
	v_pk_fma_f32 v[66:67], v[56:57], v[16:17], v[66:67] neg_lo:[0,0,1] neg_hi:[0,0,1]
	v_pk_mul_f32 v[16:17], v[52:53], v[16:17]
	v_pk_fma_f32 v[72:73], v[54:55], v[10:11], v[14:15]
	v_pk_fma_f32 v[10:11], v[56:57], v[12:13], v[16:17]
	v_cndmask_b32_e64 v12, v50, v72, s[4:5]
	s_waitcnt lgkmcnt(0)
	v_fmamk_f32 v50, v183, 0x39800000, v237
	v_cndmask_b32_e64 v13, v51, v73, s[4:5]
	v_mul_f32_e32 v51, 0x4f800000, v50
	v_cmp_gt_f32_e32 vcc, s73, v50
	v_cndmask_b32_e64 v11, v53, v11, s[4:5]
	v_cndmask_b32_e64 v16, v54, v70, s[4:5]
	v_cndmask_b32_e32 v53, v50, v51, vcc
	v_sqrt_f32_e32 v54, v53
	v_cndmask_b32_e64 v17, v55, v71, s[4:5]
	v_cndmask_b32_e64 v14, v56, v66, s[4:5]
	v_ashrrev_i32_e32 v69, 31, v68
	v_add_u32_e32 v55, -1, v54
	v_fma_f32 v56, -v55, v54, v53
	v_cmp_ge_f32_e64 s[8:9], 0, v56
	v_add_u32_e32 v56, 1, v54
	v_lshlrev_b64 v[68:69], 20, v[68:69]
	v_cndmask_b32_e64 v55, v54, v55, s[8:9]
	v_fma_f32 v54, -v56, v54, v53
	v_cmp_lt_f32_e64 s[8:9], 0, v54
	v_lshl_add_u64 v[68:69], s[16:17], 0, v[68:69]
	v_lshl_add_u64 v[68:69], v[68:69], 0, v[194:195]
	v_cndmask_b32_e64 v54, v55, v56, s[8:9]
	v_mul_f32_e32 v55, 0x37800000, v54
	v_cndmask_b32_e32 v54, v54, v55, vcc
	v_cmp_class_f32_e32 vcc, v53, v238
	v_lshl_add_u64 v[68:69], v[68:69], 0, s[26:27]
	v_lshl_add_u64 v[68:69], v[68:69], 0, v[218:219]
	v_cndmask_b32_e32 v54, v54, v53, vcc
	v_div_scale_f32 v55, s[8:9], v54, v54, v186
	v_rcp_f32_e32 v56, v55
	v_cndmask_b32_e64 v15, v57, v67, s[4:5]
	v_cvt_pk_bf16_f32 v50, v16, v17
	v_cvt_pk_bf16_f32 v51, v14, v15
	v_cndmask_b32_e64 v10, v52, v10, s[4:5]
	v_cvt_pk_bf16_f32 v52, v12, v13
	v_cvt_pk_bf16_f32 v53, v10, v11
	s_nop 1
	v_permlane16_swap_b32_e32 v50, v52
	v_permlane16_swap_b32_e32 v51, v53
	global_store_dwordx4 v[68:69], v[50:53], off
	s_nop 1
	v_fma_f32 v50, -v55, v56, 1.0
	v_fmac_f32_e32 v56, v50, v56
	v_div_scale_f32 v50, vcc, v186, v54, v186
	v_mul_f32_e32 v51, v50, v56
	v_fma_f32 v52, -v55, v51, v50
	v_fmac_f32_e32 v51, v52, v56
	v_fma_f32 v50, -v55, v51, v50
	v_div_fmas_f32 v50, v50, v56, v51
	v_ashrrev_i32_e32 v51, 12, v178
	v_cvt_f32_i32_e32 v43, v43
	v_cvt_f32_i32_e32 v45, v45
	v_cvt_f32_i32_e32 v44, v44
	v_cvt_f32_i32_e32 v42, v42
	v_add_u32_e32 v52, s31, v51
	v_cvt_f32_i32_e32 v47, v47
	v_cvt_f32_i32_e32 v46, v46
	v_cvt_f32_i32_e32 v49, v49
	v_cvt_f32_i32_e32 v48, v48
	v_mad_u64_u32 v[52:53], s[8:9], v52, 48, s[18:19]
	v_div_fixup_f32 v50, v50, v54, v186
	v_ashrrev_i32_e32 v53, 31, v52
	v_lshlrev_b64 v[52:53], 20, v[52:53]
	v_lshlrev_b32_e32 v54, 8, v178
	v_pk_mul_f32 v[44:45], v[50:51], v[44:45] op_sel_hi:[0,1]
	v_pk_mul_f32 v[42:43], v[50:51], v[42:43] op_sel_hi:[0,1]
	v_lshl_add_u64 v[52:53], s[16:17], 0, v[52:53]
	v_and_b32_e32 v194, 0xfff00, v54
	v_pk_mul_f32 v[48:49], v[50:51], v[48:49] op_sel_hi:[0,1]
	v_pk_mul_f32 v[46:47], v[50:51], v[46:47] op_sel_hi:[0,1]
	v_pk_mul_f32 v[56:57], v[106:107], v[42:43]
	v_pk_mul_f32 v[42:43], v[108:109], v[44:45]
	v_lshl_add_u64 v[52:53], v[52:53], 0, v[194:195]
	v_pk_mul_f32 v[54:55], v[110:111], v[46:47]
	v_pk_mul_f32 v[46:47], v[112:113], v[48:49]
	v_pk_mul_f32 v[44:45], v[42:43], v[8:9]
	v_pk_mul_f32 v[48:49], v[56:57], v[6:7]
	v_cvt_f32_i32_e32 v35, v35
	v_cvt_f32_i32_e32 v34, v34
	v_lshl_add_u64 v[52:53], v[52:53], 0, s[26:27]
	v_pk_fma_f32 v[48:49], v[54:55], v[2:3], v[48:49] neg_lo:[0,0,1] neg_hi:[0,0,1]
	v_pk_fma_f32 v[44:45], v[46:47], v[4:5], v[44:45] neg_lo:[0,0,1] neg_hi:[0,0,1]
	v_pk_mul_f32 v[66:67], v[42:43], v[4:5]
	v_pk_mul_f32 v[68:69], v[56:57], v[2:3]
	v_cvt_f32_i32_e32 v39, v39
	v_cvt_f32_i32_e32 v38, v38
	v_cvt_f32_i32_e32 v37, v37
	v_cvt_f32_i32_e32 v36, v36
	v_lshl_add_u64 v[52:53], v[52:53], 0, v[218:219]
	v_pk_fma_f32 v[68:69], v[54:55], v[6:7], v[68:69]
	v_pk_fma_f32 v[66:67], v[46:47], v[8:9], v[66:67]
	v_cndmask_b32_e64 v47, v47, v45, s[4:5]
	v_cndmask_b32_e64 v46, v46, v44, s[4:5]
	v_cndmask_b32_e64 v49, v55, v49, s[4:5]
	v_cndmask_b32_e64 v48, v54, v48, s[4:5]
	v_cvt_pk_bf16_f32 v54, v48, v49
	v_cvt_pk_bf16_f32 v55, v46, v47
	v_add_u32_e32 v51, s35, v51
	v_cvt_f32_i32_e32 v41, v41
	v_cvt_f32_i32_e32 v40, v40
	v_cndmask_b32_e64 v43, v43, v67, s[4:5]
	v_cndmask_b32_e64 v42, v42, v66, s[4:5]
	v_cndmask_b32_e64 v45, v57, v69, s[4:5]
	v_cndmask_b32_e64 v44, v56, v68, s[4:5]
	v_cvt_pk_bf16_f32 v56, v44, v45
	v_cvt_pk_bf16_f32 v57, v42, v43
	s_nop 1
	v_permlane16_swap_b32_e32 v54, v56
	v_permlane16_swap_b32_e32 v55, v57
	global_store_dwordx4 v[52:53], v[54:57], off
	s_nop 1
	v_mad_u64_u32 v[52:53], s[8:9], v51, 48, s[52:53]
	v_ashrrev_i32_e32 v53, 31, v52
	v_pk_mul_f32 v[34:35], v[50:51], v[34:35] op_sel_hi:[0,1]
	v_lshlrev_b64 v[52:53], 20, v[52:53]
	v_pk_mul_f32 v[38:39], v[50:51], v[38:39] op_sel_hi:[0,1]
	v_pk_mul_f32 v[36:37], v[50:51], v[36:37] op_sel_hi:[0,1]
	v_pk_mul_f32 v[34:35], v[98:99], v[34:35]
	v_lshl_add_u64 v[52:53], s[16:17], 0, v[52:53]
	v_pk_mul_f32 v[40:41], v[50:51], v[40:41] op_sel_hi:[0,1]
	v_pk_mul_f32 v[38:39], v[102:103], v[38:39]
	v_pk_mul_f32 v[36:37], v[100:101], v[36:37]
	v_pk_mul_f32 v[54:55], v[34:35], v[6:7]
	v_lshl_add_u64 v[52:53], v[52:53], 0, v[194:195]
	v_pk_mul_f32 v[40:41], v[104:105], v[40:41]
	v_pk_mul_f32 v[50:51], v[36:37], v[8:9]
	v_pk_fma_f32 v[54:55], v[38:39], v[2:3], v[54:55] neg_lo:[0,0,1] neg_hi:[0,0,1]
	v_pk_mul_f32 v[2:3], v[34:35], v[2:3]
	v_lshl_add_u64 v[52:53], v[52:53], 0, s[26:27]
	v_pk_fma_f32 v[50:51], v[40:41], v[4:5], v[50:51] neg_lo:[0,0,1] neg_hi:[0,0,1]
	v_pk_mul_f32 v[4:5], v[36:37], v[4:5]
	v_pk_fma_f32 v[56:57], v[38:39], v[6:7], v[2:3]
	v_lshl_add_u64 v[52:53], v[52:53], 0, v[218:219]
	v_pk_fma_f32 v[2:3], v[40:41], v[8:9], v[4:5]
	v_cndmask_b32_e64 v7, v41, v51, s[4:5]
	v_cndmask_b32_e64 v6, v40, v50, s[4:5]
	v_cndmask_b32_e64 v9, v39, v55, s[4:5]
	v_cndmask_b32_e64 v8, v38, v54, s[4:5]
	v_cndmask_b32_e64 v5, v35, v57, s[4:5]
	v_cndmask_b32_e64 v4, v34, v56, s[4:5]
	v_cvt_pk_bf16_f32 v34, v8, v9
	v_cvt_pk_bf16_f32 v35, v6, v7
	v_cndmask_b32_e64 v3, v37, v3, s[4:5]
	v_cndmask_b32_e64 v2, v36, v2, s[4:5]
	v_cvt_pk_bf16_f32 v36, v4, v5
	v_cvt_pk_bf16_f32 v37, v2, v3
	s_nop 1
	v_permlane16_swap_b32_e32 v34, v36
	v_permlane16_swap_b32_e32 v35, v37
	global_store_dwordx4 v[52:53], v[34:37], off
	s_nop 1
	s_cbranch_scc1 .LBB0_360
	v_pk_add_f32 v[34:35], v[176:177], 0 op_sel_hi:[1,0]
	s_lshr_b32 s4, s42, 4
	v_pk_add_f32 v[34:35], v[160:161], v[34:35]
	s_lshl_b32 s5, s40, 5
	v_pk_add_f32 v[34:35], v[144:145], v[34:35]
	s_mul_i32 s9, s4, 0x180
	v_pk_add_f32 v[34:35], v[128:129], v[34:35]
	s_and_b32 s8, s42, 15
	v_pk_add_f32 v[34:35], v[34:35], v[96:97]
	s_add_i32 s9, s9, s5
	v_pk_add_f32 v[34:35], v[80:81], v[34:35]
	s_or_b32 s4, s9, s8
	v_pk_add_f32 v[34:35], v[64:65], v[34:35]
	s_addk_i32 s4, 0xfd00
	v_pk_add_f32 v[36:37], v[48:49], v[34:35]
	s_ashr_i32 s5, s4, 31
	v_cndmask_b32_e64 v34, 0, v36, s[6:7]
	ds_bpermute_b32 v35, v230, v34
	s_lshl_b64 s[4:5], s[4:5], 9
	s_add_u32 s4, s68, s4
	s_addc_u32 s5, s69, s5
	v_cmp_eq_u32_e32 vcc, 0, v239
	s_waitcnt lgkmcnt(0)
	v_add_f32_e32 v34, v34, v35
	ds_bpermute_b32 v35, v231, v34
	s_waitcnt lgkmcnt(0)
	v_add_f32_e32 v34, v34, v35
	ds_bpermute_b32 v35, v232, v34
	s_waitcnt lgkmcnt(0)
	v_add_f32_e32 v36, v34, v35
	ds_bpermute_b32 v38, v233, v36
	v_lshl_add_u64 v[34:35], v[214:215], 2, s[4:5]
	s_and_saveexec_b64 s[4:5], vcc
	s_cbranch_execz .LBB0_329
	s_waitcnt lgkmcnt(0)
	v_add_f32_e32 v36, v36, v38
	v_mul_f32_e32 v36, 0x3b800000, v36
	global_atomic_add_f32 v[34:35], v36, off
